# combo7 + E27: ssd block-loop C.B^T score MFMAs read LDS fragments two K-steps ahead instead of one-by-one
# speedup vs baseline: 1.0483x; 1.0017x over previous
.LBB0_206:
	ds_read_b128 v[104:107], v136 offset:33792
	ds_read_b128 v[108:111], v153 offset:51200
	ds_read_b128 v[112:115], v154 offset:51200
	ds_read_b128 v[116:119], v136 offset:33856
	ds_read_b128 v[120:123], v153 offset:51264
	ds_read_b128 v[128:131], v154 offset:51264
	s_waitcnt lgkmcnt(4)
	v_mfma_f32_16x16x32_bf16 v[236:239], v[104:107], v[108:111], 0
	s_waitcnt lgkmcnt(3)
	v_mfma_f32_16x16x32_bf16 v[240:243], v[104:107], v[112:115], 0
	ds_read_b128 v[104:107], v136 offset:33920
	ds_read_b128 v[108:111], v153 offset:51328
	ds_read_b128 v[112:115], v154 offset:51328
	s_waitcnt lgkmcnt(4)
	v_mfma_f32_16x16x32_bf16 v[236:239], v[116:119], v[120:123], v[236:239]
	s_waitcnt lgkmcnt(3)
	v_mfma_f32_16x16x32_bf16 v[240:243], v[116:119], v[128:131], v[240:243]
	ds_read_b128 v[116:119], v136 offset:33984
	ds_read_b128 v[120:123], v153 offset:51392
	ds_read_b128 v[128:131], v154 offset:51392
	s_waitcnt lgkmcnt(4)
	v_mfma_f32_16x16x32_bf16 v[236:239], v[104:107], v[108:111], v[236:239]
	s_waitcnt lgkmcnt(3)
	v_mfma_f32_16x16x32_bf16 v[240:243], v[104:107], v[112:115], v[240:243]
	s_waitcnt lgkmcnt(1)
	v_mfma_f32_16x16x32_bf16 v[236:239], v[116:119], v[120:123], v[236:239]
	s_waitcnt lgkmcnt(0)
	v_mfma_f32_16x16x32_bf16 v[240:243], v[116:119], v[128:131], v[240:243]
	v_mov_b32_e32 v142, 0
	v_mov_b32_e32 v127, 0
	s_nop 5
	ds_write2_b32 v155, v236, v237 offset1:68
	ds_write2_b32 v155, v238, v239 offset0:136 offset1:204
	ds_write2_b32 v156, v240, v241 offset1:68
	ds_write2_b32 v156, v242, v243 offset0:136 offset1:204
	s_waitcnt lgkmcnt(0)
	s_barrier
	ds_read_b128 v[116:119], v152
	ds_read_b128 v[108:111], v152 offset:16
	ds_read_b128 v[112:115], v152 offset:8192
	ds_read_b128 v[104:107], v152 offset:8208
	ds_read_b32 v130, v151 offset:17408
	ds_read2_b32 v[124:125], v168 offset0:1 offset1:2
	ds_read2_b32 v[122:123], v168 offset0:3 offset1:4
	ds_read2_b32 v[120:121], v168 offset0:5 offset1:6
	ds_read_b32 v126, v168 offset:28
	s_and_saveexec_b64 s[10:11], s[0:1]
	s_cbranch_execz .LBB0_208
	s_waitcnt lgkmcnt(4)
	v_sub_f32_e32 v127, v130, v116
	v_min_f32_e32 v127, 0, v127
	v_mul_f32_e32 v127, 0x3fb8aa3b, v127
	ds_read_b32 v128, v168
	v_exp_f32_e32 v127, v127
	s_waitcnt lgkmcnt(0)
	v_mul_f32_e32 v127, v127, v128
	v_mul_f32_e32 v127, v112, v127
